# gla_scan: steady-state copy of the chunk loop with relaxed counted vmcnt waits (prologue drained once; strict loop kept for the last 3 iterations)
# speedup vs baseline: 1.0538x; 1.0016x over previous
; DI void phase_gla_scan(const Params& p, LAS unsigned char* lds) {
;     ...
;         auto qload = [&](int c, bf16x8 (&q)[8]) {
;             const char* cb = (const char*)(big + (tok0 + (size_t)c * 64) * 6400) + offq;
; #pragma unroll
;             for (int ks = 0; ks < 8; ++ks) q[ks] = *(const bf16x8*)(cb + 64 * ks);
;         };
;     ...
;         __syncthreads();
;         gload(0, rkA, rvA, rtA); lstore(0, rkA, rvA, rtA);
;         gload(1, rkA, rvA, rtA); gload(2, rkB, rvB, rtB); qload(0, qa); qload(1, qn);
;         __syncthreads();
.LBB0_584:
	s_or_b64 exec, exec, s[42:43]
	v_add_u32_e32 v4, s49, v160
	global_load_dwordx4 v[56:59], v4, s[36:37]
	global_load_dwordx4 v[60:63], v4, s[36:37] offset:64
	global_load_dwordx4 v[64:67], v4, s[36:37] offset:128
	global_load_dwordx4 v[68:71], v4, s[36:37] offset:192
	global_load_dwordx4 v[72:75], v4, s[36:37] offset:256
	global_load_dwordx4 v[80:83], v4, s[36:37] offset:320
	global_load_dwordx4 v[88:91], v4, s[36:37] offset:384
	global_load_dwordx4 v[96:99], v4, s[36:37] offset:448
	global_load_dwordx4 v[76:79], v4, s[38:39]
	global_load_dwordx4 v[84:87], v4, s[38:39] offset:64
	global_load_dwordx4 v[92:95], v4, s[38:39] offset:128
	global_load_dwordx4 v[100:103], v4, s[38:39] offset:192
	global_load_dwordx4 v[104:107], v4, s[38:39] offset:256
	global_load_dwordx4 v[108:111], v4, s[38:39] offset:320
	global_load_dwordx4 v[112:115], v4, s[38:39] offset:384
	global_load_dwordx4 v[116:119], v4, s[38:39] offset:448
	s_ashr_i32 s31, s30, 31
	s_lshl_b64 s[36:37], s[30:31], 12
	v_lshlrev_b32_e32 v2, 2, v2
	v_mov_b32_e32 v3, v131
	s_add_i32 s50, s50, s49
	v_mov_b32_e32 v5, v131
	v_lshl_add_u64 v[132:133], v[124:125], 0, v[2:3]
	v_lshl_add_u64 v[134:135], s[34:35], 0, v[130:131]
	v_add_lshl_u32 v130, s50, v129, 1
	s_lshl_b32 s24, s48, 6
	v_lshl_add_u64 v[2:3], v[122:123], 0, s[36:37]
	v_lshl_add_u64 v[136:137], s[34:35], 0, v[136:137]
	v_lshl_add_u64 v[138:139], s[34:35], 0, v[138:139]
	v_lshl_add_u64 v[140:141], s[34:35], 0, v[140:141]
	v_lshl_add_u64 v[142:143], s[34:35], 0, v[130:131]
	v_lshl_add_u64 v[144:145], s[34:35], 0, v[4:5]
	s_and_b32 s34, s24, 0xc00
	s_and_b32 s24, s24, 0x3c0
	v_lshlrev_b64 v[148:149], 12, v[2:3]
	s_lshl_b64 s[30:31], s[30:31], 24
	s_or_b32 s35, s24, s34
	v_or_b32_e32 v1, v128, v148
	s_or_b32 s30, s30, s35
	v_or_b32_e32 v1, s34, v1
	v_lshl_add_u64 v[146:147], s[30:31], 0, v[126:127]
	v_or_b32_e32 v148, s24, v1
	s_mov_b32 s24, 0
	v_mov_b32_e32 v1, v0
	v_mov_b32_e32 v2, v0
	v_mov_b32_e32 v3, v0
	v_mov_b32_e32 v4, v0
	v_mov_b32_e32 v5, v0
	v_mov_b32_e32 v6, v0
	v_mov_b32_e32 v7, v0
	v_mov_b32_e32 v8, v0
	v_mov_b32_e32 v9, v0
	v_mov_b32_e32 v10, v0
	v_mov_b32_e32 v11, v0
	v_mov_b32_e32 v12, v0
	v_mov_b32_e32 v13, v0
	v_mov_b32_e32 v14, v0
	v_mov_b32_e32 v15, v0
	s_waitcnt vmcnt(0) lgkmcnt(0)
	s_barrier
	s_branch .Lgs_586

; #define LAS __attribute__((address_space(3)))
; DI void phase_gla_scan(const Params& p, LAS unsigned char* lds) {
;     ...
;         auto lstore = [&](int buf, const u32x4 (&rk)[4], const u32x4& rv, const float& rt) {
;             LAS unsigned char* sb = lds + buf * SET;
; #pragma unroll
;             for (int i = 0; i < 4; ++i) { const int idx = tid + i * 512, row = idx >> 5, cc = idx & 31; *(LAS u32x4*)(sb + row * KR + cc * 16) = rk[i]; }
;             if (tid < 256) { const int row = tid >> 2, cc = tid & 3; *(LAS u32x4*)(sb + 64 * KR + row * VR + cc * 16) = rv; ((LAS float*)(sb + 64 * KR + 64 * VR))[tid] = __expf(rt); }
;         };
;     ...
;         for (int c = 0; c < 64; c += 2) {
;             lstore((c + 1) & 1, rkA, rvA, rtA);
.Lgs_586:
	s_waitcnt vmcnt(31)
	ds_write_b128 v185, v[20:23] offset:41984
	s_waitcnt vmcnt(30)
	ds_write_b128 v186, v[24:27] offset:41984
	s_waitcnt vmcnt(29)
	ds_write_b128 v187, v[28:31] offset:41984
	s_waitcnt vmcnt(28)
	ds_write_b128 v188, v[32:35] offset:41984
	s_and_saveexec_b64 s[30:31], s[8:9]
	s_cbranch_execz .Lgs_588
	v_mul_f32_e32 v130, 0x3fb8aa3b, v194
	v_exp_f32_e32 v130, v130
	ds_write_b128 v168, v[16:19]
	ds_write_b32 v162, v130

; DI void phase_gla_scan(const Params& p, LAS unsigned char* lds) {
;     ...
;         auto step = [&](int c, const bf16x8 (&qc)[8]) {
;             LAS unsigned char* sb = lds + (c & 1) * SET; LAS unsigned char* stb = lds + ST_OFF + (c & 1) * STB;
; #pragma unroll
;             for (int g = 0; g < 4; ++g) { const f32x4 e = *(LAS const f32x4*)(sb + 64 * KR + 64 * VR + (32 * w + 8 * g + 4 * hh) * 4);
;                 st[4 * g] *= e[0]; st[4 * g + 1] *= e[1]; st[4 * g + 2] *= e[2]; st[4 * g + 3] *= e[3]; }
; #pragma unroll
;             for (int sx = 0; sx < 4; ++sx) {
;                 LAS unsigned char* ka = sb + (16 * sx + 8 * hh + tq) * KR + (32 * w + 16 * blk + 4 * tp) * 2;
;                 LAS unsigned char* va = sb + 64 * KR + (16 * sx + 8 * hh + tq) * VR + (16 * blk + 4 * tp) * 2;
;                 const bf16x8 af = cat4(trread(ka), trread(ka + 4 * KR)), bfv = cat4(trread(va), trread(va + 4 * VR));
;                 st = mfma32(af, bfv, st);
;             }
; #pragma unroll
;             for (int g = 0; g < 4; ++g) { u32x2 wv; wv.x = pk2(st[4 * g], st[4 * g + 1]); wv.y = pk2(st[4 * g + 2], st[4 * g + 3]);
;                 *(LAS u32x2*)(stb + l32 * SR + (32 * w + 8 * g + 4 * hh) * 2) = wv; }
;             asm volatile("s_waitcnt lgkmcnt(0)" ::: "memory");
;             __builtin_amdgcn_s_barrier();
;             asm volatile("" ::: "memory");
;             f32x4 acc = {0.f, 0.f, 0.f, 0.f};
; #pragma unroll
;             for (int ks = 0; ks < 8; ++ks) {
;                 const bf16x8 bb = *(LAS const bf16x8*)(stb + (16 * nt + i16) * SR + (32 * ks + 8 * quad) * 2);
;                 acc = __builtin_amdgcn_mfma_f32_16x16x32_bf16(qc[ks], bb, acc, 0, 0, 0);
;             }
; #pragma unroll
;             for (int jj = 0; jj < 4; ++jj) ob[(tok0 + c * 64 + 16 * mt + quad * 4 + jj) * DM + h * 512 + vs * 32 + 16 * nt + i16] = f2bf(acc[jj] * (1.f / 16.f));
;         };
;         __syncthreads();
;         gload(0, rkA, rvA, rtA); lstore(0, rkA, rvA, rtA);
;         gload(1, rkA, rvA, rtA); gload(2, rkB, rvB, rtB); qload(0, qa); qload(1, qn);
;         __syncthreads();
;         for (int c = 0; c < 64; c += 2) {
;             lstore((c + 1) & 1, rkA, rvA, rtA);
;             if (c + 3 < 64) gload(c + 3, rkA, rvA, rtA);
;             step(c, qa);
;             if (c + 2 < 64) qload(c + 2, qa);
;             if (c + 2 < 64) lstore(c & 1, rkB, rvB, rtB);
.Lgs_592:
	ds_read_b128 v[198:201], v169 offset:41056
	ds_read_b128 v[202:205], v169 offset:41024
	ds_read_b128 v[206:209], v169 offset:40960
	ds_read_b128 v[210:213], v169 offset:40992
	ds_read_b64_tr_b16 v[214:215], v190
	ds_read_b64_tr_b16 v[216:217], v190 offset:2304
	ds_read_b64_tr_b16 v[218:219], v170 offset:36864
	ds_read_b64_tr_b16 v[220:221], v170 offset:37120
	s_waitcnt lgkmcnt(7)
	v_pk_mul_f32 v[12:13], v[12:13], v[198:199]
	s_waitcnt lgkmcnt(6)
	v_pk_mul_f32 v[8:9], v[8:9], v[202:203]
	s_waitcnt lgkmcnt(4)
	v_pk_mul_f32 v[4:5], v[4:5], v[210:211]
	v_pk_mul_f32 v[0:1], v[0:1], v[206:207]
	v_pk_mul_f32 v[14:15], v[14:15], v[200:201]
	v_pk_mul_f32 v[10:11], v[10:11], v[204:205]
	v_pk_mul_f32 v[6:7], v[6:7], v[212:213]
	v_pk_mul_f32 v[2:3], v[2:3], v[208:209]
	ds_read_b64_tr_b16 v[198:199], v191
	ds_read_b64_tr_b16 v[200:201], v191 offset:2304
	ds_read_b64_tr_b16 v[202:203], v171 offset:36864
	ds_read_b64_tr_b16 v[204:205], v171 offset:37120
	s_waitcnt lgkmcnt(4)
	v_mfma_f32_32x32x16_bf16 v[0:15], v[214:217], v[218:221], v[0:15]
	s_cmp_gt_u32 s24, 61
	s_cselect_b64 s[34:35], -1, 0
	s_waitcnt lgkmcnt(0)
	v_mfma_f32_32x32x16_bf16 v[0:15], v[198:201], v[202:205], v[0:15]
	ds_read_b64_tr_b16 v[198:199], v192
	ds_read_b64_tr_b16 v[200:201], v192 offset:2304
	ds_read_b64_tr_b16 v[202:203], v172 offset:36864
	ds_read_b64_tr_b16 v[204:205], v172 offset:37120
	s_waitcnt lgkmcnt(0)
	v_mfma_f32_32x32x16_bf16 v[0:15], v[198:201], v[202:205], v[0:15]
	ds_read_b64_tr_b16 v[198:199], v193
	ds_read_b64_tr_b16 v[200:201], v193 offset:2304
	ds_read_b64_tr_b16 v[202:203], v173 offset:36864
	ds_read_b64_tr_b16 v[204:205], v173 offset:37120
	s_waitcnt lgkmcnt(0)
	v_mfma_f32_32x32x16_bf16 v[0:15], v[198:201], v[202:205], v[0:15]
	s_nop 11
	v_cvt_pk_bf16_f32 v158, v0, v1
	v_cvt_pk_bf16_f32 v159, v2, v3
	v_cvt_pk_bf16_f32 v198, v4, v5
	v_cvt_pk_bf16_f32 v199, v6, v7
	v_cvt_pk_bf16_f32 v200, v8, v9
	v_cvt_pk_bf16_f32 v201, v10, v11
	v_cvt_pk_bf16_f32 v202, v12, v13
	v_cvt_pk_bf16_f32 v203, v14, v15
	ds_write2_b64 v174, v[158:159], v[198:199] offset1:2
	ds_write2_b64 v174, v[200:201], v[202:203] offset0:4 offset1:6
	s_waitcnt lgkmcnt(0)
	s_barrier
	ds_read_b128 v[198:201], v175
	ds_read_b128 v[202:205], v175 offset:64
	s_waitcnt vmcnt(27) lgkmcnt(1)
	v_mfma_f32_16x16x32_bf16 v[198:201], v[56:59], v[198:201], 0
	v_lshl_add_u64 v[158:159], s[12:13], 0, v[148:149]
	v_add_co_u32_e32 v210, vcc, s45, v158
	s_waitcnt vmcnt(26) lgkmcnt(0)
	v_mfma_f32_16x16x32_bf16 v[198:201], v[60:63], v[202:205], v[198:201]
	ds_read_b128 v[202:205], v175 offset:128
	ds_read_b128 v[206:209], v175 offset:192
	v_addc_co_u32_e32 v211, vcc, 0, v159, vcc
	s_waitcnt vmcnt(25) lgkmcnt(1)
	v_mfma_f32_16x16x32_bf16 v[198:201], v[64:67], v[202:205], v[198:201]
	ds_read_b128 v[202:205], v175 offset:256
	v_add_co_u32_e32 v212, vcc, 0x7f02000, v158
	s_waitcnt vmcnt(24) lgkmcnt(1)
	v_mfma_f32_16x16x32_bf16 v[198:201], v[68:71], v[206:209], v[198:201]
	ds_read_b128 v[206:209], v175 offset:320
	v_addc_co_u32_e32 v213, vcc, 0, v159, vcc
	s_waitcnt vmcnt(23) lgkmcnt(1)
	v_mfma_f32_16x16x32_bf16 v[198:201], v[72:75], v[202:205], v[198:201]
	ds_read_b128 v[202:205], v175 offset:384
	v_add_co_u32_e32 v158, vcc, 0x7f03000, v158
	s_waitcnt vmcnt(22) lgkmcnt(1)
	v_mfma_f32_16x16x32_bf16 v[198:201], v[80:83], v[206:209], v[198:201]
	ds_read_b128 v[206:209], v175 offset:448
	v_addc_co_u32_e32 v159, vcc, 0, v159, vcc
	s_waitcnt vmcnt(21) lgkmcnt(1)
	v_mfma_f32_16x16x32_bf16 v[198:201], v[88:91], v[202:205], v[198:201]
	s_and_b64 vcc, exec, s[34:35]
	s_waitcnt vmcnt(20) lgkmcnt(0)
	v_mfma_f32_16x16x32_bf16 v[198:201], v[96:99], v[206:209], v[198:201]
	s_nop 7
	v_mul_f32_e32 v130, 0x3d800000, v198
	v_mul_f32_e32 v197, 0x3d800000, v199
	v_mul_f32_e32 v199, 0x3d800000, v201
	v_mul_f32_e32 v198, 0x3d800000, v200
	v_cvt_pk_bf16_f32 v130, v130, s0
	v_cvt_pk_bf16_f32 v199, v199, s0
	v_cvt_pk_bf16_f32 v197, v197, s0
	v_cvt_pk_bf16_f32 v198, v198, s0
	global_store_short v[210:211], v130, off offset:-4096
	global_store_short v[210:211], v197, off
	global_store_short v[212:213], v198, off
	global_store_short v[158:159], v199, off
	v_lshl_add_u64 v[158:159], s[12:13], 0, v[144:145]
	s_cbranch_vccnz .Lgs_596
	v_add_co_u32_e32 v96, vcc, 0xc090000, v158
	s_nop 1
	v_addc_co_u32_e32 v97, vcc, 0, v159, vcc
	global_load_dwordx4 v[56:59], v[96:97], off
	global_load_dwordx4 v[60:63], v[96:97], off offset:64
	global_load_dwordx4 v[64:67], v[96:97], off offset:128
	global_load_dwordx4 v[68:71], v[96:97], off offset:192
	global_load_dwordx4 v[72:75], v[96:97], off offset:256
	global_load_dwordx4 v[80:83], v[96:97], off offset:320
	global_load_dwordx4 v[88:91], v[96:97], off offset:384
	s_nop 0
	global_load_dwordx4 v[96:99], v[96:97], off offset:448
	s_waitcnt vmcnt(28)
	ds_write_b128 v185, v[36:39]
	ds_write_b128 v186, v[40:43]
	ds_write_b128 v187, v[44:47]
	ds_write_b128 v188, v[48:51]
	s_and_saveexec_b64 s[36:37], s[8:9]
	s_cbranch_execz .Lgs_595
	v_mul_f32_e32 v130, 0x3fb8aa3b, v196
	v_exp_f32_e32 v130, v130
	ds_write_b128 v189, v[52:55] offset:36864
	ds_write_b32 v161, v130 offset:40960

; DI void phase_gla_scan(const Params& p, LAS unsigned char* lds) {
;     ...
;         auto step = [&](int c, const bf16x8 (&qc)[8]) {
;             LAS unsigned char* sb = lds + (c & 1) * SET; LAS unsigned char* stb = lds + ST_OFF + (c & 1) * STB;
; #pragma unroll
;             for (int g = 0; g < 4; ++g) { const f32x4 e = *(LAS const f32x4*)(sb + 64 * KR + 64 * VR + (32 * w + 8 * g + 4 * hh) * 4);
;                 st[4 * g] *= e[0]; st[4 * g + 1] *= e[1]; st[4 * g + 2] *= e[2]; st[4 * g + 3] *= e[3]; }
; #pragma unroll
;             for (int sx = 0; sx < 4; ++sx) {
;                 LAS unsigned char* ka = sb + (16 * sx + 8 * hh + tq) * KR + (32 * w + 16 * blk + 4 * tp) * 2;
;                 LAS unsigned char* va = sb + 64 * KR + (16 * sx + 8 * hh + tq) * VR + (16 * blk + 4 * tp) * 2;
;                 const bf16x8 af = cat4(trread(ka), trread(ka + 4 * KR)), bfv = cat4(trread(va), trread(va + 4 * VR));
;                 st = mfma32(af, bfv, st);
;             }
; #pragma unroll
;             for (int g = 0; g < 4; ++g) { u32x2 wv; wv.x = pk2(st[4 * g], st[4 * g + 1]); wv.y = pk2(st[4 * g + 2], st[4 * g + 3]);
;                 *(LAS u32x2*)(stb + l32 * SR + (32 * w + 8 * g + 4 * hh) * 2) = wv; }
;             asm volatile("s_waitcnt lgkmcnt(0)" ::: "memory");
;             __builtin_amdgcn_s_barrier();
;             asm volatile("" ::: "memory");
;             f32x4 acc = {0.f, 0.f, 0.f, 0.f};
; #pragma unroll
;             for (int ks = 0; ks < 8; ++ks) {
;                 const bf16x8 bb = *(LAS const bf16x8*)(stb + (16 * nt + i16) * SR + (32 * ks + 8 * quad) * 2);
;                 acc = __builtin_amdgcn_mfma_f32_16x16x32_bf16(qc[ks], bb, acc, 0, 0, 0);
;             }
; #pragma unroll
;             for (int jj = 0; jj < 4; ++jj) ob[(tok0 + c * 64 + 16 * mt + quad * 4 + jj) * DM + h * 512 + vs * 32 + 16 * nt + i16] = f2bf(acc[jj] * (1.f / 16.f));
;         };
;         __syncthreads();
;         gload(0, rkA, rvA, rtA); lstore(0, rkA, rvA, rtA);
;         gload(1, rkA, rvA, rtA); gload(2, rkB, rvB, rtB); qload(0, qa); qload(1, qn);
;         __syncthreads();
;         for (int c = 0; c < 64; c += 2) {
;             lstore((c + 1) & 1, rkA, rvA, rtA);
;             if (c + 3 < 64) gload(c + 3, rkA, rvA, rtA);
;             step(c, qa);
;             if (c + 2 < 64) qload(c + 2, qa);
;             if (c + 2 < 64) lstore(c & 1, rkB, rvB, rtB);
.Lgs_600:
	ds_read_b128 v[150:153], v176 offset:96
	ds_read_b128 v[154:157], v176 offset:64
	ds_read_b128 v[198:201], v176 offset:32
	ds_read_b128 v[202:205], v176
	s_waitcnt lgkmcnt(3)
	v_pk_mul_f32 v[12:13], v[12:13], v[150:151]
	v_pk_mul_f32 v[14:15], v[14:15], v[152:153]
	ds_read_b64_tr_b16 v[150:151], v190 offset:41984
	ds_read_b64_tr_b16 v[152:153], v190 offset:44288
	s_waitcnt lgkmcnt(4)
	v_pk_mul_f32 v[8:9], v[8:9], v[154:155]
	s_waitcnt lgkmcnt(3)
	v_pk_mul_f32 v[4:5], v[4:5], v[198:199]
	v_pk_mul_f32 v[10:11], v[10:11], v[156:157]
	v_pk_mul_f32 v[6:7], v[6:7], v[200:201]
	s_waitcnt lgkmcnt(2)
	v_pk_mul_f32 v[2:3], v[2:3], v[204:205]
	v_pk_mul_f32 v[0:1], v[0:1], v[202:203]
	ds_read_b64_tr_b16 v[154:155], v177
	ds_read_b64_tr_b16 v[156:157], v177 offset:256
	ds_read_b64_tr_b16 v[198:199], v191 offset:41984
	ds_read_b64_tr_b16 v[200:201], v191 offset:44288
	ds_read_b64_tr_b16 v[202:203], v179
	ds_read_b64_tr_b16 v[204:205], v179 offset:256
	s_waitcnt lgkmcnt(4)
	v_mfma_f32_32x32x16_bf16 v[0:15], v[150:153], v[154:157], v[0:15]
	s_waitcnt lgkmcnt(0)
	v_mfma_f32_32x32x16_bf16 v[0:15], v[198:201], v[202:205], v[0:15]
	ds_read_b64_tr_b16 v[150:151], v192 offset:41984
	ds_read_b64_tr_b16 v[152:153], v192 offset:44288
	ds_read_b64_tr_b16 v[154:155], v180
	ds_read_b64_tr_b16 v[156:157], v180 offset:256
	ds_read_b64_tr_b16 v[198:199], v193 offset:41984
	ds_read_b64_tr_b16 v[200:201], v193 offset:44288
	ds_read_b64_tr_b16 v[202:203], v182
	ds_read_b64_tr_b16 v[204:205], v182 offset:256
	s_waitcnt lgkmcnt(4)
	v_mfma_f32_32x32x16_bf16 v[0:15], v[150:153], v[154:157], v[0:15]
	s_waitcnt lgkmcnt(0)
	v_mfma_f32_32x32x16_bf16 v[0:15], v[198:201], v[202:205], v[0:15]
	v_lshl_add_u64 v[202:203], s[12:13], 0, v[146:147]
	v_add_co_u32_e32 v204, vcc, s46, v202
	s_nop 1
	v_addc_co_u32_e32 v205, vcc, 0, v203, vcc
	v_add_co_u32_e32 v206, vcc, 0x7f42000, v202
	s_nop 5
	v_cvt_pk_bf16_f32 v150, v0, v1
	v_cvt_pk_bf16_f32 v151, v2, v3
	v_cvt_pk_bf16_f32 v152, v4, v5
	v_cvt_pk_bf16_f32 v153, v6, v7
	v_cvt_pk_bf16_f32 v154, v8, v9
	v_cvt_pk_bf16_f32 v155, v10, v11
	v_cvt_pk_bf16_f32 v156, v12, v13
	v_cvt_pk_bf16_f32 v157, v14, v15
	ds_write2_b64 v183, v[150:151], v[152:153] offset1:2
	ds_write2_b64 v183, v[154:155], v[156:157] offset0:4 offset1:6
	s_waitcnt lgkmcnt(0)
	s_barrier
	ds_read_b128 v[150:153], v184
	ds_read_b128 v[154:157], v184 offset:64
	s_waitcnt vmcnt(27) lgkmcnt(1)
	v_mfma_f32_16x16x32_bf16 v[150:153], v[76:79], v[150:153], 0
	v_addc_co_u32_e32 v207, vcc, 0, v203, vcc
	s_waitcnt vmcnt(26) lgkmcnt(0)
	v_mfma_f32_16x16x32_bf16 v[150:153], v[84:87], v[154:157], v[150:153]
	ds_read_b128 v[154:157], v184 offset:128
	ds_read_b128 v[198:201], v184 offset:192
	s_waitcnt vmcnt(25) lgkmcnt(1)
	v_mfma_f32_16x16x32_bf16 v[150:153], v[92:95], v[154:157], v[150:153]
	ds_read_b128 v[154:157], v184 offset:256
	s_waitcnt vmcnt(24) lgkmcnt(1)
	v_mfma_f32_16x16x32_bf16 v[150:153], v[100:103], v[198:201], v[150:153]
	ds_read_b128 v[198:201], v184 offset:320
	s_waitcnt vmcnt(23) lgkmcnt(1)
	v_mfma_f32_16x16x32_bf16 v[150:153], v[104:107], v[154:157], v[150:153]
	ds_read_b128 v[154:157], v184 offset:384
	s_waitcnt vmcnt(22) lgkmcnt(1)
	v_mfma_f32_16x16x32_bf16 v[150:153], v[108:111], v[198:201], v[150:153]
	ds_read_b128 v[198:201], v184 offset:448
	s_waitcnt vmcnt(21) lgkmcnt(1)
	v_mfma_f32_16x16x32_bf16 v[150:153], v[112:115], v[154:157], v[150:153]
	s_waitcnt vmcnt(20) lgkmcnt(0)
	v_mfma_f32_16x16x32_bf16 v[150:153], v[116:119], v[198:201], v[150:153]
	s_nop 7
	v_mul_f32_e32 v130, 0x3d800000, v150
	v_mul_f32_e32 v150, 0x3d800000, v151
	v_mul_f32_e32 v151, 0x3d800000, v152
	v_cvt_pk_bf16_f32 v130, v130, s0
	v_cvt_pk_bf16_f32 v150, v150, s0
	v_cvt_pk_bf16_f32 v151, v151, s0
	global_store_short v[204:205], v130, off offset:-4096
	global_store_short v[204:205], v150, off
	global_store_short v[206:207], v151, off
	v_add_co_u32_e32 v150, vcc, 0x7f43000, v202
	v_mul_f32_e32 v152, 0x3d800000, v153
	s_nop 0
	v_addc_co_u32_e32 v151, vcc, 0, v203, vcc
	v_cvt_pk_bf16_f32 v152, v152, s0
	s_andn2_b64 vcc, exec, s[30:31]
	global_store_short v[150:151], v152, off
	s_cbranch_vccnz .Lgs_585
	v_add_co_u32_e32 v116, vcc, 0xc158000, v158
	s_nop 1
	v_addc_co_u32_e32 v117, vcc, 0, v159, vcc
	global_load_dwordx4 v[76:79], v[116:117], off
	global_load_dwordx4 v[84:87], v[116:117], off offset:64
	global_load_dwordx4 v[92:95], v[116:117], off offset:128
	global_load_dwordx4 v[100:103], v[116:117], off offset:192
	global_load_dwordx4 v[104:107], v[116:117], off offset:256
	global_load_dwordx4 v[108:111], v[116:117], off offset:320
	global_load_dwordx4 v[112:115], v[116:117], off offset:384
	s_nop 0
	global_load_dwordx4 v[116:119], v[116:117], off offset:448
	s_branch .Lgs_585
.Lgs_585:
	s_add_i32 s24, s24, 2
	v_lshl_add_u64 v[134:135], v[134:135], 0, s[26:27]
	v_lshl_add_u64 v[136:137], v[136:137], 0, s[26:27]
	v_lshl_add_u64 v[138:139], v[138:139], 0, s[26:27]
	v_lshl_add_u64 v[140:141], v[140:141], 0, s[26:27]
	v_lshl_add_u64 v[142:143], v[142:143], 0, s[26:27]
	v_lshl_add_u64 v[144:145], v[144:145], 0, s[26:27]
	v_lshl_add_u64 v[146:147], v[146:147], 0, s[28:29]
	v_lshl_add_u64 v[148:149], v[148:149], 0, s[28:29]
	s_cmp_lt_u32 s24, 58
	s_cbranch_scc1 .Lgs_586
	s_branch .LBB0_586
